# split down-GEMM phase: half of the workgroups run their context split-K quarter unit first, the other half last, so residual epilogue bursts of the halves do not coincide
# speedup vs baseline: 1.0020x; 1.0016x over previous
.LBB0_841:
	s_andn2_b64 vcc, exec, s[0:1]
	s_cbranch_vccnz .LBB0_932
	s_mov_b32 s98, 0
	s_mov_b32 s99, 0
	s_mov_b32 s100, 0
	s_bitcmp1_b32 s69, 3
	s_cbranch_scc0 .Lgrpa_dn
	s_mov_b32 s98, s68
	s_ashr_i32 s54, s69, 4
	s_addk_i32 s54, 0x80
	s_bfe_u32 s73, s69, 0x20002
	s_and_b32 s99, s69, 3
	s_mul_i32 s99, s99, 11
	s_and_b32 s100, s69, 1
	s_add_i32 s99, s99, s100
	s_cmp_eq_u32 s100, 0
	s_cselect_b32 s100, 12, 10
.Lgrpa_dn:
	v_ashrrev_i32_e32 v1, 31, v8
	v_lshrrev_b32_e32 v1, 26, v1
	v_add_u32_e32 v1, v8, v1
	v_ashrrev_i32_e32 v9, 6, v1
	v_bfe_i32 v1, v8, 27, 1
	v_lshlrev_b32_e32 v0, 4, v8
	v_lshrrev_b32_e32 v1, 22, v1
	v_add_u32_e32 v1, v0, v1
	v_and_b32_e32 v1, 0xfffffc00, v1
	v_sub_u32_e32 v1, v0, v1
	v_lshrrev_b32_e32 v2, 4, v1
	v_bitop3_b32 v1, v2, v1, 32 bitop3:0x6c
	v_ashrrev_i32_e32 v3, 31, v1
	v_lshrrev_b32_e32 v3, 26, v3
	v_lshlrev_b32_e32 v2, 3, v9
	v_add_u32_e32 v3, v1, v3
	v_and_b32_e32 v2, -16, v2
	v_ashrrev_i32_e32 v11, 6, v3
	v_and_b32_e32 v3, 0xc0, v3
	v_add_u32_e32 v2, v11, v2
	v_lshlrev_b32_e32 v4, 5, v9
	v_sub_u32_e32 v1, v1, v3
	v_and_b32_e32 v10, 32, v4
	v_ashrrev_i16_sdwa v1, v219, sext(v1) dst_sel:DWORD dst_unused:UNUSED_PAD src0_sel:DWORD src1_sel:BYTE_0
	v_lshlrev_b32_e32 v3, 1, v2
	v_lshrrev_b32_e32 v4, 2, v2
	v_and_b32_e32 v5, 3, v11
	s_mov_b32 s0, 0xffffe0
	v_bfe_i32 v12, v1, 0, 16
	v_and_b32_e32 v3, 24, v3
	v_and_b32_e32 v4, 4, v4
	v_and_or_b32 v5, v2, s0, v5
	s_movk_i32 s1, 0xb00
	v_add_u32_e32 v1, v10, v12
	v_or3_b32 v3, v5, v4, v3
	v_mul_lo_u32 v2, v2, s1
	v_add_lshl_u32 v168, v1, v2, 1
	v_mul_u32_u24_e32 v2, 0xb00, v3
	v_add_u32_e32 v0, 0x2000, v0
	v_add_lshl_u32 v170, v2, v1, 1
	v_ashrrev_i32_e32 v1, 31, v0
	v_lshrrev_b32_e32 v1, 22, v1
	v_add_u32_e32 v1, v0, v1
	v_ashrrev_i32_e32 v13, 10, v1
	v_mul_i32_i24_e32 v1, 0x400, v13
	v_sub_u32_e32 v0, v0, v1
	v_lshrrev_b32_e32 v1, 4, v0
	v_bitop3_b32 v0, v1, v0, 32 bitop3:0x6c
	v_ashrrev_i32_e32 v2, 31, v0
	v_lshrrev_b32_e32 v2, 26, v2
	v_lshlrev_b32_e32 v1, 3, v13
	v_add_u32_e32 v2, v0, v2
	v_and_b32_e32 v1, -16, v1
	v_ashrrev_i32_e32 v15, 6, v2
	s_ashr_i32 s3, s2, 6
	v_add_u32_e32 v1, v15, v1
	v_lshlrev_b32_e32 v3, 5, v13
	v_and_b32_e32 v2, 0xc0, v2
	v_and_b32_e32 v4, 3, v15
	v_and_b32_e32 v14, 32, v3
	v_sub_u32_e32 v0, v0, v2
	v_lshlrev_b32_e32 v2, 1, v1
	v_lshrrev_b32_e32 v3, 2, v1
	v_and_or_b32 v4, v1, s0, v4
	v_mul_lo_u32 v1, v1, s1
	s_ashr_i32 s4, s2, 8
	s_lshl_b32 s72, s3, 10
	s_mul_i32 s1, s73, 0x160000
	v_ashrrev_i16_sdwa v0, v219, sext(v0) dst_sel:DWORD dst_unused:UNUSED_PAD src0_sel:DWORD src1_sel:BYTE_0
	s_mul_hi_i32 s0, s73, 0x160000
	s_add_u32 s40, s58, s1
	v_bfe_i32 v16, v0, 0, 16
	v_and_b32_e32 v2, 24, v2
	v_and_b32_e32 v3, 4, v3
	s_addc_u32 s41, s59, s0
	s_lshl_b32 s32, s99, 7
	s_add_u32 s40, s40, s32
	s_addc_u32 s41, s41, 0
	s_add_i32 s74, s72, 0
	v_add_u32_e32 v0, v14, v16
	v_or3_b32 v2, v4, v3, v2
	s_add_i32 m0, s74, 0x10000
	v_add_lshl_u32 v172, v0, v1, 1
	v_mul_u32_u24_e32 v1, 0xb00, v2
	global_load_lds_dwordx4 v170, s[40:41]
	s_add_i32 m0, s74, 0x12000
	v_add_lshl_u32 v174, v1, v0, 1
	s_add_u32 s0, s40, 0xb0000
	global_load_lds_dwordx4 v174, s[40:41]
	s_addc_u32 s1, s41, 0
	s_add_i32 m0, s74, 0x14000
	s_mul_i32 s6, s54, 0x160000
	global_load_lds_dwordx4 v170, s[0:1]
	s_add_i32 m0, s74, 0x16000
	s_mul_hi_i32 s5, s54, 0x160000
	s_add_u32 s8, s42, s6
	s_addc_u32 s9, s43, s5
	s_lshl_b32 s32, s99, 7
	s_add_u32 s8, s8, s32
	s_addc_u32 s9, s9, 0
	s_add_i32 s75, s74, 0x2000
	global_load_lds_dwordx4 v174, s[0:1]
	s_mov_b32 m0, s74
	s_add_u32 s0, s8, 0xb0000
	global_load_lds_dwordx4 v168, s[8:9]
	s_mov_b32 m0, s75
	s_addc_u32 s1, s9, 0
	s_add_i32 s80, s74, 0x4000
	global_load_lds_dwordx4 v172, s[8:9]
	s_mov_b32 m0, s80
	s_add_i32 s81, s74, 0x6000
	global_load_lds_dwordx4 v168, s[0:1]
	s_mov_b32 m0, s81
	v_writelane_b32 v255, s26, 8
	global_load_lds_dwordx4 v172, s[0:1]
	s_nop 0
	v_writelane_b32 v255, s27, 9
	v_writelane_b32 v255, s94, 15
	v_mov_b32_e32 v171, v177
	v_mov_b32_e32 v175, v177
	v_writelane_b32 v255, s95, 16
	v_mov_b32_e32 v169, v177
	v_mov_b32_e32 v173, v177
	s_cmp_eq_u32 s4, 1
	v_writelane_b32 v255, s66, 5
	v_lshl_add_u64 v[6:7], s[40:41], 0, v[170:171]
	v_lshl_add_u64 v[4:5], s[40:41], 0, v[174:175]
	v_lshl_add_u64 v[0:1], s[8:9], 0, v[168:169]
	s_cselect_b64 s[0:1], -1, 0
	s_cmp_lg_u32 s4, 1
	v_lshl_add_u64 v[2:3], s[8:9], 0, v[172:173]
	s_cbranch_scc1 .LBB0_844
	s_barrier
.LBB0_844:
	s_and_b32 s82, s3, 3
	s_add_i32 m0, s74, 0x18000
	v_lshl_add_u64 v[6:7], v[6:7], 0, s[34:35]
	s_lshl_b32 s3, s4, 13
	s_lshl_b32 s5, s82, 5
	s_lshl_b32 s16, s82, 12
	s_waitcnt vmcnt(2)
	s_barrier
	global_load_lds_dwordx4 v[6:7], off
	v_lshl_add_u64 v[4:5], v[4:5], 0, s[34:35]
	s_add_i32 m0, s74, 0x1a000
	s_add_i32 s83, s74, 0x8000
	s_add_i32 s91, s74, 0xa000
	global_load_lds_dwordx4 v[4:5], off
	v_lshl_add_u64 v[0:1], v[0:1], 0, s[34:35]
	s_mov_b32 m0, s83
	s_add_u32 s6, s40, 0xb0080
	global_load_lds_dwordx4 v[0:1], off
	v_lshl_add_u64 v[0:1], v[2:3], 0, s[34:35]
	s_mov_b32 m0, s91
	s_addc_u32 s7, s41, 0
	global_load_lds_dwordx4 v[0:1], off
	s_add_i32 m0, s74, 0x1c000
	v_lshl_add_u64 v[0:1], s[6:7], 0, v[170:171]
	global_load_lds_dwordx4 v[0:1], off
	v_lshl_add_u64 v[0:1], s[6:7], 0, v[174:175]
	s_add_i32 m0, s74, 0x1e000
	v_lshlrev_b32_e32 v3, 2, v8
	global_load_lds_dwordx4 v[0:1], off
	v_and_b32_e32 v0, 15, v8
	v_bfe_u32 v1, v8, 4, 2
	v_lshlrev_b32_e32 v2, 6, v0
	v_lshl_or_b32 v2, v1, 4, v2
	v_and_b32_e32 v3, 32, v3
	s_cmpk_lt_u32 s2, 0x100
	v_bitop3_b32 v4, v2, s3, v3 bitop3:0xde
	s_cselect_b64 s[22:23], -1, 0
	s_and_b32 s3, s69, 3
	s_ashr_i32 s2, s69, 4
	s_mul_i32 s94, s3, 11
	s_and_b32 s3, s69, 1
	s_addk_i32 s2, 0x80
	s_bfe_u32 s93, s69, 0x20002
	s_add_i32 s94, s94, s3
	v_lshlrev_b32_e32 v0, 10, v0
	s_cmp_eq_u32 s3, 0
	s_movk_i32 s3, 0xb00
	v_lshl_or_b32 v229, v1, 3, s5
	v_lshl_or_b32 v230, s4, 16, v0
	v_cmp_eq_u32_e64 s[4:5], 0, v1
	v_lshrrev_b32_e32 v1, 1, v13
	v_mul_lo_u32 v0, v15, s3
	s_mov_b32 s17, 0xb000
	v_mad_u64_u32 v[0:1], s[6:7], v1, s17, v[0:1]
	v_or_b32_e32 v0, v0, v14
	v_add_lshl_u32 v176, v0, v16, 1
	v_lshrrev_b32_e32 v1, 1, v9
	v_mul_lo_u32 v0, v11, s3
	v_mad_u64_u32 v[0:1], s[6:7], v1, s17, v[0:1]
	v_bitop3_b32 v228, v2, s16, v3 bitop3:0xde
	s_waitcnt vmcnt(6)
	s_cselect_b32 s62, 12, 10
	s_ashr_i32 s37, s68, 31
	s_ashr_i32 s16, s69, 31
	s_mov_b64 s[26:27], 0xb0080
	v_or_b32_e32 v0, v0, v10
	s_cmp_lg_u64 s[48:49], 0
	v_lshl_add_u64 v[182:183], v[176:177], 0, s[26:27]
	v_add_lshl_u32 v176, v0, v12, 1
	v_or_b32_e32 v231, v229, v230
	s_mov_b32 s44, s100
	s_cselect_b64 s[24:25], -1, 0
	v_lshl_add_u64 v[184:185], v[176:177], 0, s[26:27]
	s_mov_b32 s63, 44
	v_add_u32_e32 v232, 0, v4
	s_mov_b32 s55, s99
	s_mov_b32 s17, 0
	s_cmp_lg_u32 s100, 0
	s_cselect_b32 s63, s100, s63
	s_barrier
	s_branch .LBB0_847

.LBB0_847:
	s_mov_b32 s3, s17
	s_add_i32 s17, s17, 1
	s_cmp_eq_u32 s98, 0
	s_cbranch_scc1 .Lhdr_orig_dn
	s_cmp_lt_u32 s3, 2
	s_cbranch_scc1 .LBB0_851
	s_mov_b64 s[6:7], 0
	s_mov_b64 s[28:29], 0
	s_mov_b32 s92, s51
	s_mov_b32 s3, s50
	s_mov_b32 s26, s27
	s_mov_b32 s95, s52
	s_branch .LBB0_850
.Lhdr_orig_dn:
	s_cmp_lg_u32 s3, 0
	s_cbranch_scc0 .LBB0_851
	s_mov_b64 s[6:7], 0
	s_cmp_lg_u32 s17, 2
	s_mov_b64 s[28:29], 0
	s_mov_b32 s92, s51
	s_mov_b32 s3, s50
	s_mov_b32 s26, s27
	s_mov_b32 s95, s52
	s_cbranch_scc1 .LBB0_850
	s_mov_b64 s[28:29], -1
	s_mov_b32 s92, s2
	s_mov_b32 s3, s93
	s_mov_b32 s26, s94
	s_mov_b32 s95, s62

.LBB0_851:
.LBB0_852:
	s_mul_i32 s3, s17, s37
	s_mul_hi_u32 s6, s17, s68
	s_add_i32 s3, s6, s3
	s_mul_i32 s6, s17, s68
	s_add_u32 s6, s6, s69
	s_addc_u32 s7, s3, s16
	s_sub_u32 s6, s6, s98
	s_subb_u32 s7, s7, 0
	v_mov_b64_e32 v[0:1], 0x1ff
	v_cmp_gt_i64_e32 vcc, s[6:7], v[0:1]
	s_mov_b64 s[28:29], 0
	s_cbranch_vccnz .LBB0_858
	s_ashr_i32 s3, s6, 31
	s_lshr_b32 s3, s3, 29
	s_add_i32 s3, s6, s3
	s_and_b32 s7, s3, -8
	s_sub_i32 s26, s6, s7
	s_cmp_gt_i32 s26, -1
	s_mov_b64 s[6:7], -1
	s_cbranch_scc0 .LBB0_855
	s_lshl_b32 s27, s26, 6
	s_mov_b64 s[6:7], 0

	.amdhsa_kernel _Z14fwd_megakernel6Params
		.amdhsa_group_segment_fixed_size 0
		.amdhsa_private_segment_fixed_size 0
		.amdhsa_kernarg_size 448
		.amdhsa_user_sgpr_count 2
		.amdhsa_user_sgpr_dispatch_ptr 0
		.amdhsa_user_sgpr_queue_ptr 0
		.amdhsa_user_sgpr_kernarg_segment_ptr 1
		.amdhsa_user_sgpr_dispatch_id 0
		.amdhsa_user_sgpr_kernarg_preload_length 0
		.amdhsa_user_sgpr_kernarg_preload_offset 0
		.amdhsa_user_sgpr_private_segment_size 0
		.amdhsa_uses_dynamic_stack 0
		.amdhsa_enable_private_segment 0
		.amdhsa_system_sgpr_workgroup_id_x 1
		.amdhsa_system_sgpr_workgroup_id_y 0
		.amdhsa_system_sgpr_workgroup_id_z 0
		.amdhsa_system_sgpr_workgroup_info 0
		.amdhsa_system_vgpr_workitem_id 2
		.amdhsa_next_free_vgpr 256
		.amdhsa_next_free_sgpr 102
		.amdhsa_accum_offset 256
		.amdhsa_reserve_vcc 1
		.amdhsa_float_round_mode_32 0
		.amdhsa_float_round_mode_16_64 0
		.amdhsa_float_denorm_mode_32 3
		.amdhsa_float_denorm_mode_16_64 3
		.amdhsa_dx10_clamp 1
		.amdhsa_ieee_mode 1
		.amdhsa_fp16_overflow 0
		.amdhsa_tg_split 0
		.amdhsa_exception_fp_ieee_invalid_op 0
		.amdhsa_exception_fp_denorm_src 0
		.amdhsa_exception_fp_ieee_div_zero 0
		.amdhsa_exception_fp_ieee_overflow 0
		.amdhsa_exception_fp_ieee_underflow 0
		.amdhsa_exception_fp_ieee_inexact 0
		.amdhsa_exception_int_div_zero 0
	.end_amdhsa_kernel

amdhsa.kernels:
  - .agpr_count:     0
    .args:
      - .offset:         0
        .size:           192
        .value_kind:     by_value
      - .offset:         192
        .size:           4
        .value_kind:     hidden_block_count_x
      - .offset:         196
        .size:           4
        .value_kind:     hidden_block_count_y
      - .offset:         200
        .size:           4
        .value_kind:     hidden_block_count_z
      - .offset:         204
        .size:           2
        .value_kind:     hidden_group_size_x
      - .offset:         206
        .size:           2
        .value_kind:     hidden_group_size_y
      - .offset:         208
        .size:           2
        .value_kind:     hidden_group_size_z
      - .offset:         210
        .size:           2
        .value_kind:     hidden_remainder_x
      - .offset:         212
        .size:           2
        .value_kind:     hidden_remainder_y
      - .offset:         214
        .size:           2
        .value_kind:     hidden_remainder_z
      - .offset:         232
        .size:           8
        .value_kind:     hidden_global_offset_x
      - .offset:         240
        .size:           8
        .value_kind:     hidden_global_offset_y
      - .offset:         248
        .size:           8
        .value_kind:     hidden_global_offset_z
      - .offset:         256
        .size:           2
        .value_kind:     hidden_grid_dims
      - .offset:         280
        .size:           8
        .value_kind:     hidden_multigrid_sync_arg
      - .offset:         312
        .size:           4
        .value_kind:     hidden_dynamic_lds_size
    .group_segment_fixed_size: 0
    .kernarg_segment_align: 8
    .kernarg_segment_size: 448
    .language:       OpenCL C
    .language_version:
      - 2
      - 0
    .max_flat_workgroup_size: 512
    .name:           _Z14fwd_megakernel6Params
    .private_segment_fixed_size: 0
    .sgpr_count:     108
    .sgpr_spill_count: 31
    .symbol:         _Z14fwd_megakernel6Params.kd
    .uniform_work_group_size: 1
    .uses_dynamic_stack: false
    .vgpr_count:     256
    .vgpr_spill_count: 0
    .wavefront_size: 64
